# post_attn units: all loads hoisted and next unit prefetched, DPP row reduce, LDS double buffer (one barrier per unit)
# speedup vs baseline: 1.0244x; 1.0184x over previous
.LBB0_1097:
	s_andn2_b64 vcc, exec, s[0:1]
	s_cbranch_vccnz .LBB0_1099
	s_cmp_lg_u32 s10, s50
	s_cbranch_scc1 .Lpa_have
	v_lshrrev_b32_e32 v0, 4, v232
	v_mul_u32_u24_e32 v112, 0x3800, v0
	v_and_b32_e32 v1, 15, v232
	v_lshl_add_u32 v112, v1, 4, v112
	v_lshrrev_b32_e32 v2, 3, v232
	v_mul_u32_u24_e32 v113, 0x3800, v2
	v_and_b32_e32 v3, 7, v232
	v_lshl_add_u32 v113, v3, 5, v113
	v_lshlrev_b32_e32 v114, 6, v3
	v_lshlrev_b32_e32 v4, 3, v232
	v_and_b32_e32 v4, 56, v4
	v_mul_u32_u24_e32 v115, 0x210, v4
	v_lshrrev_b32_e32 v5, 1, v232
	v_and_b32_e32 v5, 4, v5
	v_lshl_or_b32 v5, v0, 3, v5
	v_add_u32_e32 v115, v115, v5
	v_mul_u32_u24_e32 v116, 0x210, v2
	v_add_u32_e32 v116, v116, v114
	s_lshr_b32 s2, s10, 10
	s_and_b32 s0, s10, 0x3ff
	s_lshr_b32 s0, s0, 8
	s_lshl_b32 s0, s0, 12
	s_and_b32 s1, s10, 63
	s_lshl_b32 s1, s1, 6
	s_or_b32 s0, s0, s1
	s_mul_i32 s0, s0, 0x3800
	s_lshr_b32 s1, s10, 6
	s_and_b32 s1, s1, 3
	s_lshl_b32 s1, s1, 8
	s_add_u32 s0, s0, s1
	s_lshl_b32 s12, s2, 11
	s_add_u32 s12, s12, 0x1800
	s_add_u32 s12, s12, s0
	s_lshl_b32 s13, s2, 10
	s_add_u32 s13, s13, s0
	s_cmp_lg_u32 s2, 0
	s_cselect_b64 s[0:1], s[4:5], s[6:7]
	v_add_u32_e32 v16, s12, v112
	v_lshl_add_u64 v[0:1], v[16:17], 0, s[82:83]
	global_load_dwordx4 v[64:67], v[0:1], off
	v_add_u32_e32 v16, 0x70000, v16
	v_lshl_add_u64 v[0:1], v[16:17], 0, s[82:83]
	global_load_dwordx4 v[68:71], v[0:1], off
	v_add_u32_e32 v16, s13, v113
	v_lshl_add_u64 v[96:97], v[16:17], 0, s[82:83]
	global_load_dwordx4 v[72:75], v[96:97], off offset:16
	global_load_dwordx4 v[76:79], v[96:97], off
	global_load_dwordx4 v[80:83], v114, s[0:1] offset:48
	global_load_dwordx4 v[84:87], v114, s[0:1] offset:32
	global_load_dwordx4 v[88:91], v114, s[0:1] offset:16
	global_load_dwordx4 v[92:95], v114, s[0:1]
	s_waitcnt vmcnt(0)
	s_branch .Lpa_go
.Lpa_have:
	s_waitcnt vmcnt(2)
.Lpa_go:
	s_lshr_b32 s2, s10, 8
	s_and_b32 s2, s2, 1
	s_mul_i32 s2, s2, 0x8800
	v_add_u32_e32 v100, s2, v115
	v_add_u32_e32 v103, 0x400, v100
	v_add_u32_e32 v104, 0x800, v100
	v_add_u32_e32 v105, 0xc00, v100
	v_add_u32_e32 v106, s2, v116
	v_lshlrev_b32_e32 v101, 16, v64
	v_and_b32_e32 v102, 0xffff0000, v64
	ds_write2_b32 v100, v101, v102 offset1:132
	v_lshlrev_b32_e32 v101, 16, v65
	v_and_b32_e32 v102, 0xffff0000, v65
	ds_write2_b32 v103, v101, v102 offset0:8 offset1:140
	v_lshlrev_b32_e32 v101, 16, v66
	v_and_b32_e32 v102, 0xffff0000, v66
	ds_write2_b32 v104, v101, v102 offset0:16 offset1:148
	v_lshlrev_b32_e32 v101, 16, v67
	v_and_b32_e32 v102, 0xffff0000, v67
	ds_write2_b32 v105, v101, v102 offset0:24 offset1:156
	v_lshlrev_b32_e32 v107, 16, v68
	v_and_b32_e32 v108, 0xffff0000, v68
	ds_write2_b32 v100, v107, v108 offset0:64 offset1:196
	v_lshlrev_b32_e32 v107, 16, v69
	v_and_b32_e32 v108, 0xffff0000, v69
	ds_write2_b32 v103, v107, v108 offset0:72 offset1:204
	v_lshlrev_b32_e32 v107, 16, v70
	v_and_b32_e32 v108, 0xffff0000, v70
	ds_write2_b32 v104, v107, v108 offset0:80 offset1:212
	v_lshlrev_b32_e32 v107, 16, v71
	v_and_b32_e32 v108, 0xffff0000, v71
	ds_write2_b32 v105, v107, v108 offset0:88 offset1:220
	v_mov_b64_e32 v[8:9], v[72:73]
	v_mov_b64_e32 v[10:11], v[74:75]
	v_mov_b64_e32 v[34:35], v[76:77]
	v_mov_b64_e32 v[36:37], v[78:79]
	v_mov_b64_e32 v[18:19], v[80:81]
	v_mov_b64_e32 v[20:21], v[82:83]
	v_mov_b64_e32 v[26:27], v[84:85]
	v_mov_b64_e32 v[28:29], v[86:87]
	v_mov_b64_e32 v[30:31], v[88:89]
	v_mov_b64_e32 v[32:33], v[90:91]
	v_mov_b64_e32 v[38:39], v[92:93]
	v_mov_b64_e32 v[40:41], v[94:95]
	v_mov_b64_e32 v[44:45], v[96:97]
	s_waitcnt lgkmcnt(0)
	s_barrier
	s_add_i32 s11, s10, s62
	s_cmpk_lt_u32 s11, 0x800
	s_cbranch_scc0 .Lpa_nopf
	s_lshr_b32 s2, s11, 10
	s_and_b32 s0, s11, 0x3ff
	s_lshr_b32 s0, s0, 8
	s_lshl_b32 s0, s0, 12
	s_and_b32 s1, s11, 63
	s_lshl_b32 s1, s1, 6
	s_or_b32 s0, s0, s1
	s_mul_i32 s0, s0, 0x3800
	s_lshr_b32 s1, s11, 6
	s_and_b32 s1, s1, 3
	s_lshl_b32 s1, s1, 8
	s_add_u32 s0, s0, s1
	s_lshl_b32 s12, s2, 11
	s_add_u32 s12, s12, 0x1800
	s_add_u32 s12, s12, s0
	s_lshl_b32 s13, s2, 10
	s_add_u32 s13, s13, s0
	s_cmp_lg_u32 s2, 0
	s_cselect_b64 s[0:1], s[4:5], s[6:7]
	v_add_u32_e32 v16, s12, v112
	v_lshl_add_u64 v[0:1], v[16:17], 0, s[82:83]
	global_load_dwordx4 v[64:67], v[0:1], off
	v_add_u32_e32 v16, 0x70000, v16
	v_lshl_add_u64 v[0:1], v[16:17], 0, s[82:83]
	global_load_dwordx4 v[68:71], v[0:1], off
	v_add_u32_e32 v16, s13, v113
	v_lshl_add_u64 v[96:97], v[16:17], 0, s[82:83]
	global_load_dwordx4 v[72:75], v[96:97], off offset:16
	global_load_dwordx4 v[76:79], v[96:97], off
	global_load_dwordx4 v[80:83], v114, s[0:1] offset:48
	global_load_dwordx4 v[84:87], v114, s[0:1] offset:32
	global_load_dwordx4 v[88:91], v114, s[0:1] offset:16
	global_load_dwordx4 v[92:95], v114, s[0:1]
.Lpa_nopf:
	ds_read_b128 v[22:25], v106
	ds_read_b128 v[12:15], v106 offset:16
	ds_read_b128 v[4:7], v106 offset:32
	ds_read_b128 v[0:3], v106 offset:48
	s_waitcnt lgkmcnt(3)
	v_pk_mul_f32 v[100:101], v[22:23], v[22:23]
	v_pk_fma_f32 v[100:101], v[24:25], v[24:25], v[100:101]
	s_waitcnt lgkmcnt(2)
	v_pk_fma_f32 v[100:101], v[12:13], v[12:13], v[100:101]
	v_pk_fma_f32 v[100:101], v[14:15], v[14:15], v[100:101]
	s_waitcnt lgkmcnt(1)
	v_pk_fma_f32 v[100:101], v[4:5], v[4:5], v[100:101]
	v_pk_fma_f32 v[100:101], v[6:7], v[6:7], v[100:101]
	s_waitcnt lgkmcnt(0)
	v_pk_fma_f32 v[100:101], v[0:1], v[0:1], v[100:101]
	v_pk_fma_f32 v[100:101], v[2:3], v[2:3], v[100:101]
	s_nop 0
	v_add_f32_e32 v100, v100, v101
	s_nop 1
	v_add_f32_dpp v100, v100, v100 quad_perm:[1,0,3,2] row_mask:0xf bank_mask:0xf
	s_nop 1
	v_add_f32_dpp v100, v100, v100 quad_perm:[2,3,0,1] row_mask:0xf bank_mask:0xf
	s_nop 1
	v_add_f32_dpp v100, v100, v100 row_half_mirror row_mask:0xf bank_mask:0xf
	s_nop 0
	v_fmamk_f32 v100, v100, 0x3c000000, v236
	v_cmp_gt_f32_e32 vcc, s27, v100
	v_mul_f32_e32 v101, 0x4b800000, v100
	s_nop 0
	v_cndmask_b32_e32 v100, v100, v101, vcc
	v_rsq_f32_e32 v100, v100
	s_nop 0
	v_mul_f32_e32 v101, 0x45800000, v100
	v_cndmask_b32_e32 v42, v100, v101, vcc
	v_pk_mul_f32 v[22:23], v[22:23], v[42:43] op_sel_hi:[1,0]
	v_pk_mul_f32 v[24:25], v[24:25], v[42:43] op_sel_hi:[1,0]
	v_pk_mul_f32 v[12:13], v[12:13], v[42:43] op_sel_hi:[1,0]
	v_pk_mul_f32 v[14:15], v[14:15], v[42:43] op_sel_hi:[1,0]
	v_pk_mul_f32 v[4:5], v[4:5], v[42:43] op_sel_hi:[1,0]
	v_pk_mul_f32 v[6:7], v[6:7], v[42:43] op_sel_hi:[1,0]
	v_pk_mul_f32 v[0:1], v[0:1], v[42:43] op_sel_hi:[1,0]
	v_pk_mul_f32 v[2:3], v[2:3], v[42:43] op_sel_hi:[1,0]
	v_pk_mul_f32 v[0:1], v[0:1], v[18:19]
	v_pk_mul_f32 v[4:5], v[26:27], v[4:5]
	v_lshlrev_b32_e32 v46, 16, v34
	v_mul_f32_e32 v16, 0xbfb8aa3b, v46
	v_exp_f32_e32 v16, v16
	v_and_b32_e32 v47, 0xffff0000, v34
	v_lshlrev_b32_e32 v34, 16, v35
	v_pk_mul_f32 v[22:23], v[38:39], v[22:23]
	v_add_f32_e32 v16, 1.0, v16
	v_rcp_f32_e32 v48, v16
	v_mul_f32_e32 v16, 0xbfb8aa3b, v47
	v_exp_f32_e32 v16, v16
	v_and_b32_e32 v35, 0xffff0000, v35
	v_pk_mul_f32 v[24:25], v[40:41], v[24:25]
	v_pk_mul_f32 v[12:13], v[30:31], v[12:13]
	v_add_f32_e32 v16, 1.0, v16
	v_rcp_f32_e32 v49, v16
	v_mul_f32_e32 v16, 0xbfb8aa3b, v34
	v_exp_f32_e32 v16, v16
	v_pk_mul_f32 v[14:15], v[32:33], v[14:15]
	v_pk_mul_f32 v[38:39], v[48:49], v[46:47]
	v_pk_mul_f32 v[6:7], v[28:29], v[6:7]
	v_add_f32_e32 v16, 1.0, v16
	v_pk_mul_f32 v[22:23], v[38:39], v[22:23]
	v_rcp_f32_e32 v38, v16
	v_mul_f32_e32 v16, 0xbfb8aa3b, v35
	v_exp_f32_e32 v16, v16
	v_cvt_pk_bf16_f32 v22, v22, v23
	v_pk_mul_f32 v[2:3], v[2:3], v[20:21]
	v_add_f32_e32 v16, 1.0, v16
	v_rcp_f32_e32 v39, v16
	s_nop 0
	v_pk_mul_f32 v[34:35], v[38:39], v[34:35]
	s_nop 0
	v_pk_mul_f32 v[24:25], v[34:35], v[24:25]
	s_nop 0
	v_cvt_pk_bf16_f32 v23, v24, v25
	v_lshlrev_b32_e32 v24, 16, v36
	v_mul_f32_e32 v16, 0xbfb8aa3b, v24
	v_exp_f32_e32 v16, v16
	v_and_b32_e32 v25, 0xffff0000, v36
	v_add_f32_e32 v16, 1.0, v16
	v_rcp_f32_e32 v34, v16
	v_mul_f32_e32 v16, 0xbfb8aa3b, v25
	v_exp_f32_e32 v16, v16
	s_nop 0
	v_add_f32_e32 v16, 1.0, v16
	v_rcp_f32_e32 v35, v16
	s_nop 0
	v_pk_mul_f32 v[24:25], v[34:35], v[24:25]
	s_nop 0
	v_pk_mul_f32 v[12:13], v[24:25], v[12:13]
	s_nop 0
	v_cvt_pk_bf16_f32 v24, v12, v13
	v_lshlrev_b32_e32 v12, 16, v37
	v_mul_f32_e32 v16, 0xbfb8aa3b, v12
	v_exp_f32_e32 v16, v16
	v_and_b32_e32 v13, 0xffff0000, v37
	v_add_f32_e32 v16, 1.0, v16
	v_rcp_f32_e32 v30, v16
	v_mul_f32_e32 v16, 0xbfb8aa3b, v13
	v_exp_f32_e32 v16, v16
	s_nop 0
	v_add_f32_e32 v16, 1.0, v16
	v_rcp_f32_e32 v31, v16
	s_nop 0
	v_pk_mul_f32 v[12:13], v[30:31], v[12:13]
	s_nop 0
	v_pk_mul_f32 v[12:13], v[12:13], v[14:15]
	s_nop 0
	v_cvt_pk_bf16_f32 v25, v12, v13
	v_lshlrev_b32_e32 v12, 16, v8
	v_and_b32_e32 v13, 0xffff0000, v8
	v_mul_f32_e32 v8, 0xbfb8aa3b, v12
	v_exp_f32_e32 v8, v8
	s_nop 0
	v_add_f32_e32 v8, 1.0, v8
	v_rcp_f32_e32 v14, v8
	v_mul_f32_e32 v8, 0xbfb8aa3b, v13
	v_exp_f32_e32 v8, v8
	s_nop 0
	v_add_f32_e32 v8, 1.0, v8
	v_rcp_f32_e32 v15, v8
	v_lshlrev_b32_e32 v8, 16, v9
	v_and_b32_e32 v9, 0xffff0000, v9
	v_pk_mul_f32 v[12:13], v[14:15], v[12:13]
	s_nop 0
	v_pk_mul_f32 v[4:5], v[12:13], v[4:5]
	s_nop 0
	v_cvt_pk_bf16_f32 v4, v4, v5
	v_mul_f32_e32 v5, 0xbfb8aa3b, v8
	v_exp_f32_e32 v5, v5
	s_nop 0
	v_add_f32_e32 v5, 1.0, v5
	v_rcp_f32_e32 v12, v5
	v_mul_f32_e32 v5, 0xbfb8aa3b, v9
	v_exp_f32_e32 v5, v5
	s_nop 0
	v_add_f32_e32 v5, 1.0, v5
	v_rcp_f32_e32 v13, v5
	s_nop 0
	v_pk_mul_f32 v[8:9], v[12:13], v[8:9]
	s_nop 0
	v_pk_mul_f32 v[6:7], v[8:9], v[6:7]
	s_nop 0
	v_cvt_pk_bf16_f32 v5, v6, v7
	v_lshlrev_b32_e32 v6, 16, v10
	v_and_b32_e32 v7, 0xffff0000, v10
	v_mul_f32_e32 v8, 0xbfb8aa3b, v6
	v_mul_f32_e32 v9, 0xbfb8aa3b, v7
	v_exp_f32_e32 v8, v8
	v_exp_f32_e32 v9, v9
	v_add_f32_e32 v8, 1.0, v8
	v_add_f32_e32 v9, 1.0, v9
	v_rcp_f32_e32 v8, v8
	v_rcp_f32_e32 v9, v9
	s_nop 0
	v_pk_mul_f32 v[6:7], v[8:9], v[6:7]
	s_nop 0
	v_pk_mul_f32 v[0:1], v[6:7], v[0:1]
	s_nop 0
	v_cvt_pk_bf16_f32 v6, v0, v1
	v_lshlrev_b32_e32 v0, 16, v11
	v_mul_f32_e32 v7, 0xbfb8aa3b, v0
	v_exp_f32_e32 v7, v7
	v_and_b32_e32 v1, 0xffff0000, v11
	v_add_f32_e32 v7, 1.0, v7
	v_rcp_f32_e32 v8, v7
	v_mul_f32_e32 v7, 0xbfb8aa3b, v1
	v_exp_f32_e32 v7, v7
	s_nop 0
	v_add_f32_e32 v7, 1.0, v7
	v_rcp_f32_e32 v9, v7
	s_nop 0
	v_pk_mul_f32 v[0:1], v[8:9], v[0:1]
	s_nop 0
	v_pk_mul_f32 v[0:1], v[0:1], v[2:3]
	s_nop 0
	v_cvt_pk_bf16_f32 v7, v0, v1
	global_store_dwordx4 v[44:45], v[22:25], off
	global_store_dwordx4 v[44:45], v[4:7], off offset:16
	s_cmpk_eq_u32 s62, 0x100
	s_cbranch_scc1 .Lpa_end
	s_waitcnt lgkmcnt(0)
	s_barrier
.Lpa_end:
.LBB0_1099:
	s_mov_b64 s[0:1], 0
.LBB0_1100:
	s_andn2_b64 vcc, exec, s[0:1]
	s_cbranch_vccnz .LBB0_1102
	s_nop 0
